# NSA top-16 selection by bitwise threshold search (16th largest key per token, integer compares, bit-identical selection) instead of all-pairs rank counting
# speedup vs baseline: 1.0297x; 1.0078x over previous
; #define LAS __attribute__((address_space(3)))
; __device__ __forceinline__ void nsa_item(LAS unsigned char* lds, const NsaPtrs& P, int b, int g, int qb, int tid) {
;     ...
;     {
;         int tid_k = tid; asm volatile("" : "+v"(tid_k)); const int tk = tid_k >> 3, part = tid_k & 7;
;         unsigned v[16]; int cnt[16];
;         LAS unsigned* impu = (LAS unsigned*)imp;
; #pragma unroll
;         for (int jj = 0; jj < 16; ++jj) { const int j = part * 16 + jj; const bool forced = (j == 0) || (j == qb) || (j == qb - 1);
;             const unsigned key = forced ? 0x7fffff80u : (__float_as_uint(fmaxf(imp[tk * ISTR + j], 0.f)) & 0xffffff80u); v[jj] = key | (unsigned)(127 - j); cnt[jj] = 0; }
;         __syncthreads();
; #pragma unroll
;         for (int jj = 0; jj < 16; ++jj) impu[tk * ISTR + part * 16 + jj] = v[jj];
;         __syncthreads();
;         for (int k = 0; k <= qb; ++k) { const unsigned vk = impu[tk * ISTR + k];
; #pragma unroll
;             for (int jj = 0; jj < 16; ++jj) cnt[jj] += (vk > v[jj]) ? 1 : 0; }
;         unsigned bits = 0u;
; #pragma unroll
;         for (int jj = 0; jj < 16; ++jj) { const int j = part * 16 + jj; if (j <= qb && cnt[jj] < 16) bits |= (1u << jj); }
;         ((LAS unsigned short*)(lds + OFF_SEL))[tk * 8 + part] = (unsigned short)bits;
;     }
.LBB0_1071:
	s_or_b64 exec, exec, s[6:7]
	v_sub_u32_e32 v0, v2, v47
	v_sub_u32_e32 v12, v12, v37
	v_sub_u32_e32 v3, v3, v33
	v_add_u32_e32 v2, 0x7f, v0
	v_sub_u32_e32 v0, v16, v46
	v_sub_u32_e32 v15, v15, v44
	v_sub_u32_e32 v14, v14, v41
	v_sub_u32_e32 v13, v13, v39
	v_add_u32_e32 v24, 0x7f, v12
	v_sub_u32_e32 v11, v11, v35
	v_sub_u32_e32 v5, v5, v7
	v_add_u32_e32 v12, 0x7f, v3
	v_sub_u32_e32 v3, v19, v48
	s_add_i32 s10, s72, 1
	v_add_u32_e32 v16, 0x7f, v0
	v_sub_u32_e32 v0, v17, v45
	v_add_u32_e32 v18, 0x7f, v15
	v_sub_u32_e32 v6, v6, v42
	v_add_u32_e32 v20, 0x7f, v14
	v_sub_u32_e32 v4, v4, v40
	v_add_u32_e32 v22, 0x7f, v13
	v_sub_u32_e32 v10, v10, v38
	v_sub_u32_e32 v8, v8, v36
	v_add_u32_e32 v26, 0x7f, v11
	v_sub_u32_e32 v9, v9, v34
	v_add_u32_e32 v28, 0x7f, v5
	v_add_u32_e32 v30, 0x7f, v3
	s_cmp_lg_u32 s72, 0
	v_add_u32_e32 v0, 0x7f, v0
	v_add_u32_e32 v6, 0x7f, v6
	v_add_u32_e32 v4, 0x7f, v4
	v_add_u32_e32 v10, 0x7f, v10
	v_add_u32_e32 v8, 0x7f, v8
	v_add_u32_e32 v14, 0x7f, v9
	v_lshl_add_u32 v17, v1, 6, v49
	v_mov_b32_e32 v13, v28
	v_mov_b32_e32 v15, v26
	v_mov_b32_e32 v9, v24
	v_mov_b32_e32 v11, v22
	v_mov_b32_e32 v5, v20
	v_mov_b32_e32 v7, v18
	v_mov_b32_e32 v1, v16
	v_mov_b32_e32 v3, v30
	s_cselect_b64 s[8:9], -1, 0
	s_cmp_eq_u32 s72, 0
	s_mov_b32 s11, 0
	v_mov_b32_e32 v51, 0
	s_cmp_lt_u32 s72, 16
	s_cbranch_scc1 .Ltopk_sel
	v_sub_u32_e32 v50, s72, v33
	v_cmp_le_i32_e64 s[12:13], 0, v50
	v_cmp_le_i32_e64 s[14:15], 1, v50
	v_cmp_le_i32_e64 s[20:21], 2, v50
	v_cndmask_b32_e64 v12, 0, v12, s[12:13]
	v_cmp_le_i32_e64 s[12:13], 3, v50
	v_cndmask_b32_e64 v28, 0, v28, s[14:15]
	v_cmp_le_i32_e64 s[14:15], 4, v50
	v_cndmask_b32_e64 v14, 0, v14, s[20:21]
	v_cmp_le_i32_e64 s[20:21], 5, v50
	v_cndmask_b32_e64 v26, 0, v26, s[12:13]
	v_cmp_le_i32_e64 s[12:13], 6, v50
	v_cndmask_b32_e64 v8, 0, v8, s[14:15]
	v_cmp_le_i32_e64 s[14:15], 7, v50
	v_cndmask_b32_e64 v24, 0, v24, s[20:21]
	v_cmp_le_i32_e64 s[20:21], 8, v50
	v_cndmask_b32_e64 v10, 0, v10, s[12:13]
	v_cmp_le_i32_e64 s[12:13], 9, v50
	v_cndmask_b32_e64 v22, 0, v22, s[14:15]
	v_cmp_le_i32_e64 s[14:15], 10, v50
	v_cndmask_b32_e64 v4, 0, v4, s[20:21]
	v_cmp_le_i32_e64 s[20:21], 11, v50
	v_cndmask_b32_e64 v20, 0, v20, s[12:13]
	v_cmp_le_i32_e64 s[12:13], 12, v50
	v_cndmask_b32_e64 v6, 0, v6, s[14:15]
	v_cmp_le_i32_e64 s[14:15], 13, v50
	v_cndmask_b32_e64 v18, 0, v18, s[20:21]
	v_cmp_le_i32_e64 s[20:21], 14, v50
	v_cndmask_b32_e64 v0, 0, v0, s[12:13]
	v_cmp_le_i32_e64 s[12:13], 15, v50
	s_nop 1
	v_cndmask_b32_e64 v16, 0, v16, s[14:15]
	v_cndmask_b32_e64 v2, 0, v2, s[20:21]
	v_cndmask_b32_e64 v30, 0, v30, s[12:13]
	v_bfrev_b32_e32 v54, -2
	s_mov_b32 s6, 0x40000000
.Ltopk_loop:
	v_or_b32_e32 v52, s6, v51
	v_mov_b32_e32 v53, 0
	v_cmp_ge_u32_e64 s[12:13], v12, v52
	v_cmp_ge_u32_e64 s[14:15], v28, v52
	v_cmp_ge_u32_e64 s[20:21], v14, v52
	v_addc_co_u32_e64 v53, s[60:61], 0, v53, s[12:13]
	v_cmp_ge_u32_e64 s[12:13], v26, v52
	v_addc_co_u32_e64 v53, s[60:61], 0, v53, s[14:15]
	v_cmp_ge_u32_e64 s[14:15], v8, v52
	v_addc_co_u32_e64 v53, s[60:61], 0, v53, s[20:21]
	v_cmp_ge_u32_e64 s[20:21], v24, v52
	v_addc_co_u32_e64 v53, s[60:61], 0, v53, s[12:13]
	v_cmp_ge_u32_e64 s[12:13], v10, v52
	v_addc_co_u32_e64 v53, s[60:61], 0, v53, s[14:15]
	v_cmp_ge_u32_e64 s[14:15], v22, v52
	v_addc_co_u32_e64 v53, s[60:61], 0, v53, s[20:21]
	v_cmp_ge_u32_e64 s[20:21], v4, v52
	v_addc_co_u32_e64 v53, s[60:61], 0, v53, s[12:13]
	v_cmp_ge_u32_e64 s[12:13], v20, v52
	v_addc_co_u32_e64 v53, s[60:61], 0, v53, s[14:15]
	v_cmp_ge_u32_e64 s[14:15], v6, v52
	v_addc_co_u32_e64 v53, s[60:61], 0, v53, s[20:21]
	v_cmp_ge_u32_e64 s[20:21], v18, v52
	v_addc_co_u32_e64 v53, s[60:61], 0, v53, s[12:13]
	v_cmp_ge_u32_e64 s[12:13], v0, v52
	v_addc_co_u32_e64 v53, s[60:61], 0, v53, s[14:15]
	v_cmp_ge_u32_e64 s[14:15], v16, v52
	v_addc_co_u32_e64 v53, s[60:61], 0, v53, s[20:21]
	v_cmp_ge_u32_e64 s[20:21], v2, v52
	v_addc_co_u32_e64 v53, s[60:61], 0, v53, s[12:13]
	v_cmp_ge_u32_e64 s[12:13], v30, v52
	s_nop 1
	v_addc_co_u32_e64 v53, s[60:61], 0, v53, s[14:15]
	v_addc_co_u32_e64 v53, s[60:61], 0, v53, s[20:21]
	v_addc_co_u32_e64 v53, s[60:61], 0, v53, s[12:13]
	s_nop 1
	v_add_u32_dpp v53, v53, v53 quad_perm:[1,0,3,2] row_mask:0xf bank_mask:0xf
	s_nop 1
	v_add_u32_dpp v53, v53, v53 quad_perm:[2,3,0,1] row_mask:0xf bank_mask:0xf
	s_nop 1
	v_add_u32_dpp v53, v53, v53 row_half_mirror row_mask:0xf bank_mask:0xf
	s_lshr_b32 s6, s6, 1
	v_cmp_le_u32_e32 vcc, 16, v53
	s_nop 1
	v_cndmask_b32_e32 v51, v51, v52, vcc
	v_cndmask_b32_e32 v54, v54, v53, vcc
	s_cmp_eq_u32 s6, 0
	s_cbranch_scc1 .Ltopk_sel
	v_cmp_lt_u32_e32 vcc, 16, v54
	s_cbranch_vccnz .Ltopk_loop
.Ltopk_sel:
	v_cmp_ge_u32_e64 s[12:13], v12, v51
	v_cmp_ge_u32_e64 s[14:15], v28, v51
	v_cmp_ge_u32_e64 s[20:21], v14, v51
	v_cndmask_b32_e64 v31, 16, 0, s[12:13]
	v_cmp_ge_u32_e64 s[12:13], v26, v51
	v_cndmask_b32_e64 v29, 16, 0, s[14:15]
	v_cmp_ge_u32_e64 s[14:15], v8, v51
	v_cndmask_b32_e64 v27, 16, 0, s[20:21]
	v_cmp_ge_u32_e64 s[20:21], v24, v51
	v_cndmask_b32_e64 v25, 16, 0, s[12:13]
	v_cmp_ge_u32_e64 s[12:13], v10, v51
	v_cndmask_b32_e64 v23, 16, 0, s[14:15]
	v_cmp_ge_u32_e64 s[14:15], v22, v51
	v_cndmask_b32_e64 v21, 16, 0, s[20:21]
	v_cmp_ge_u32_e64 s[20:21], v4, v51
	v_cndmask_b32_e64 v19, 16, 0, s[12:13]
	v_cmp_ge_u32_e64 s[12:13], v20, v51
	v_cndmask_b32_e64 v17, 16, 0, s[14:15]
	v_cmp_ge_u32_e64 s[14:15], v6, v51
	v_cndmask_b32_e64 v15, 16, 0, s[20:21]
	v_cmp_ge_u32_e64 s[20:21], v18, v51
	v_cndmask_b32_e64 v13, 16, 0, s[12:13]
	v_cmp_ge_u32_e64 s[12:13], v0, v51
	v_cndmask_b32_e64 v11, 16, 0, s[14:15]
	v_cmp_ge_u32_e64 s[14:15], v16, v51
	v_cndmask_b32_e64 v9, 16, 0, s[20:21]
	v_cmp_ge_u32_e64 s[20:21], v2, v51
	v_cndmask_b32_e64 v7, 16, 0, s[12:13]
	v_cmp_ge_u32_e64 s[12:13], v30, v51
	s_nop 1
	v_cndmask_b32_e64 v5, 16, 0, s[14:15]
	v_cndmask_b32_e64 v3, 16, 0, s[20:21]
	v_cndmask_b32_e64 v1, 16, 0, s[12:13]
